# one-pass LRU: look-back done by waves 0-1 only (packed (A,h) records, carry-in shared through LDS)
# speedup vs baseline: 1.0265x; 1.0060x over previous
; __device__ __forceinline__ float softplusf_(float x) { return fmaxf(x, 0.f) + log1pf(__expf(-fabsf(x))); }
; __device__ __forceinline__ float fsig0(float x) { return __builtin_amdgcn_rcpf(1.0f + __expf(-x)); }
; template <int PASS> __device__ void lru_phase(const Params& p, unsigned char* smem) {
;     ...
;         {
;             const int ch = 16 * wave + (lane & 15), cgl = jb * 128 + ch;
;             const float ba_ = jb_fixed ? hb_a : p.in[6][cgl], bx_ = jb_fixed ? hb_x : p.in[8][cgl], sp = jb_fixed ? hsp : softplusf_(-p.in[9][cgl]);
; #pragma unroll
;             for (int m = 0; m < 4; ++m)
; #pragma unroll
;                 for (int r = 0; r < 4; ++r) { const int t = 16 * m + 4 * (lane >> 4) + r;
;                     const float rg = fsig0(accA[m][r] + ba_), ig = fsig0(accX[m][r] + bx_);
;                     const float la = -8.0f * rg * sp, a = __expf(la), u = __builtin_amdgcn_sqrtf(fmaxf(1.0f - a * a, 0.f)) * (ig * xcf[t * 132 + ch]);
;                     As[t * 132 + ch] = a; Us[t * 132 + ch] = u; }
.LBB0_572:
	s_waitcnt vmcnt(0)
	v_add_f32_e32 v66, v96, v100
	v_add_f32_e32 v96, v97, v100
	v_mul_f32_e32 v96, 0xbfb8aa3b, v96
	v_exp_f32_e32 v96, v96
	v_mul_f32_e32 v66, 0xbfb8aa3b, v66
	v_exp_f32_e32 v66, v66
	v_add_f32_e32 v93, v93, v101
	v_add_f32_e32 v96, 1.0, v96
	v_rcp_f32_e32 v96, v96
	v_add_f32_e32 v66, 1.0, v66
	v_mul_f32_e32 v93, 0xbfb8aa3b, v93
	v_rcp_f32_e32 v66, v66
	v_mul_f32_e32 v96, 0xc1000000, v96
	v_mul_f32_e32 v96, v96, v102
	v_mul_f32_e32 v96, 0x3fb8aa3b, v96
	v_exp_f32_e32 v93, v93
	v_exp_f32_e32 v96, v96
	ds_read2_b32 v[104:105], v141 offset1:132
	v_mul_f32_e32 v66, 0xc1000000, v66
	v_add_f32_e32 v93, 1.0, v93
	v_fma_f32 v103, -v96, v96, 1.0
	v_mul_f32_e32 v66, v66, v102
	v_rcp_f32_e32 v93, v93
	v_max_f32_e32 v103, 0, v103
	v_add_f32_e32 v98, v98, v100
	v_mul_f32_e32 v66, 0x3fb8aa3b, v66
	v_sqrt_f32_e32 v103, v103
	v_mul_f32_e32 v98, 0xbfb8aa3b, v98
	v_exp_f32_e32 v66, v66
	v_exp_f32_e32 v98, v98
	s_waitcnt lgkmcnt(0)
	v_mul_f32_e32 v93, v93, v105
	v_mul_f32_e32 v93, v93, v103
	v_add_u32_e32 v103, 0x8400, v141
	v_fma_f32 v97, -v66, v66, 1.0
	ds_write2_b32 v103, v66, v96 offset1:132
	v_add_f32_e32 v66, 1.0, v98
	v_rcp_f32_e32 v66, v66
	v_add_f32_e32 v94, v94, v101
	v_add_f32_e32 v98, v99, v100
	v_mul_f32_e32 v94, 0xbfb8aa3b, v94
	v_mul_f32_e32 v66, 0xc1000000, v66
	v_mul_f32_e32 v66, v66, v102
	v_mul_f32_e32 v66, 0x3fb8aa3b, v66
	v_mul_f32_e32 v98, 0xbfb8aa3b, v98
	v_exp_f32_e32 v94, v94
	v_exp_f32_e32 v66, v66
	v_exp_f32_e32 v98, v98
	ds_write_b32 v143, v93
	v_add_f32_e32 v93, 1.0, v94
	v_fma_f32 v94, -v66, v66, 1.0
	ds_read_b32 v96, v141 offset:1056
	ds_write_b32 v141, v66 offset:34848
	v_add_f32_e32 v66, 1.0, v98
	v_rcp_f32_e32 v93, v93
	v_max_f32_e32 v94, 0, v94
	v_rcp_f32_e32 v66, v66
	v_sqrt_f32_e32 v94, v94
	s_waitcnt lgkmcnt(1)
	v_mul_f32_e32 v93, v93, v96
	v_add_f32_e32 v88, v88, v100
	v_mul_f32_e32 v66, 0xc1000000, v66
	v_mul_f32_e32 v93, v94, v93
	v_add_f32_e32 v94, v95, v101
	v_mul_f32_e32 v66, v66, v102
	v_mul_f32_e32 v94, 0xbfb8aa3b, v94
	v_mul_f32_e32 v66, 0x3fb8aa3b, v66
	v_mul_f32_e32 v88, 0xbfb8aa3b, v88
	v_exp_f32_e32 v94, v94
	v_exp_f32_e32 v66, v66
	v_exp_f32_e32 v88, v88
	ds_write_b32 v144, v93
	v_add_f32_e32 v93, 1.0, v94
	v_fma_f32 v94, -v66, v66, 1.0
	ds_write_b32 v141, v66 offset:35376
	v_add_f32_e32 v66, 1.0, v88
	v_rcp_f32_e32 v66, v66
	ds_read_b32 v95, v141 offset:1584
	v_rcp_f32_e32 v93, v93
	v_max_f32_e32 v94, 0, v94
	v_mul_f32_e32 v66, 0xc1000000, v66
	v_mul_f32_e32 v66, v66, v102
	v_add_f32_e32 v89, v89, v100
	v_sqrt_f32_e32 v94, v94
	v_mul_f32_e32 v66, 0x3fb8aa3b, v66
	v_mul_f32_e32 v89, 0xbfb8aa3b, v89
	v_exp_f32_e32 v66, v66
	v_exp_f32_e32 v89, v89
	s_waitcnt lgkmcnt(0)
	v_mul_f32_e32 v93, v93, v95
	v_add_f32_e32 v84, v84, v101
	v_mul_f32_e32 v93, v94, v93
	v_mul_f32_e32 v84, 0xbfb8aa3b, v84
	v_exp_f32_e32 v84, v84
	ds_write_b32 v145, v93
	v_fma_f32 v88, -v66, v66, 1.0
	ds_write_b32 v141, v66 offset:42240
	v_add_f32_e32 v66, 1.0, v89
	v_rcp_f32_e32 v66, v66
	v_add_f32_e32 v84, 1.0, v84
	ds_read_b32 v93, v141 offset:8448
	v_rcp_f32_e32 v84, v84
	v_max_f32_e32 v88, 0, v88
	v_mul_f32_e32 v66, 0xc1000000, v66
	v_sqrt_f32_e32 v88, v88
	v_add_f32_e32 v85, v85, v101
	v_mul_f32_e32 v66, v66, v102
	v_add_f32_e32 v89, v90, v100
	v_mul_f32_e32 v85, 0xbfb8aa3b, v85
	v_mul_f32_e32 v66, 0x3fb8aa3b, v66
	v_mul_f32_e32 v89, 0xbfb8aa3b, v89
	v_exp_f32_e32 v85, v85
	v_exp_f32_e32 v66, v66
	v_exp_f32_e32 v89, v89
	s_waitcnt lgkmcnt(0)
	v_mul_f32_e32 v84, v84, v93
	v_mul_f32_e32 v84, v88, v84
	ds_write_b32 v146, v84
	v_add_f32_e32 v84, 1.0, v85
	v_fma_f32 v85, -v66, v66, 1.0
	ds_read_b32 v88, v141 offset:8976
	ds_write_b32 v141, v66 offset:42768
	v_add_f32_e32 v66, 1.0, v89
	v_rcp_f32_e32 v84, v84
	v_max_f32_e32 v85, 0, v85
	v_rcp_f32_e32 v66, v66
	v_sqrt_f32_e32 v85, v85
	s_waitcnt lgkmcnt(1)
	v_mul_f32_e32 v84, v84, v88
	v_add_f32_e32 v88, v91, v100
	v_mul_f32_e32 v66, 0xc1000000, v66
	v_mul_f32_e32 v84, v85, v84
	v_add_f32_e32 v85, v86, v101
	v_mul_f32_e32 v66, v66, v102
	v_mul_f32_e32 v85, 0xbfb8aa3b, v85
	v_mul_f32_e32 v66, 0x3fb8aa3b, v66
	v_mul_f32_e32 v88, 0xbfb8aa3b, v88
	v_exp_f32_e32 v85, v85
	v_exp_f32_e32 v66, v66
	v_exp_f32_e32 v88, v88
	ds_write_b32 v147, v84
	v_add_f32_e32 v84, 1.0, v85
	v_fma_f32 v85, -v66, v66, 1.0
	ds_read_b32 v86, v141 offset:9504
	ds_write_b32 v141, v66 offset:43296
	v_add_f32_e32 v66, 1.0, v88
	v_rcp_f32_e32 v84, v84
	v_max_f32_e32 v85, 0, v85
	v_rcp_f32_e32 v66, v66
	v_sqrt_f32_e32 v85, v85
	s_waitcnt lgkmcnt(1)
	v_mul_f32_e32 v84, v84, v86
	v_add_f32_e32 v80, v80, v100
	v_mul_f32_e32 v66, 0xc1000000, v66
	v_mul_f32_e32 v84, v85, v84
	v_add_f32_e32 v85, v87, v101
	v_mul_f32_e32 v66, v66, v102
	v_mul_f32_e32 v85, 0xbfb8aa3b, v85
	v_mul_f32_e32 v66, 0x3fb8aa3b, v66
	v_mul_f32_e32 v80, 0xbfb8aa3b, v80
	v_exp_f32_e32 v85, v85
	v_exp_f32_e32 v66, v66
	v_exp_f32_e32 v80, v80
	ds_write_b32 v148, v84
	v_add_f32_e32 v84, 1.0, v85
	v_fma_f32 v85, -v66, v66, 1.0
	ds_write_b32 v141, v66 offset:43824
	v_add_f32_e32 v66, 1.0, v80
	v_rcp_f32_e32 v66, v66
	ds_read_b32 v86, v141 offset:10032
	v_rcp_f32_e32 v84, v84
	v_max_f32_e32 v85, 0, v85
	v_mul_f32_e32 v66, 0xc1000000, v66
	v_mul_f32_e32 v66, v66, v102
	v_add_f32_e32 v81, v81, v100
	v_sqrt_f32_e32 v85, v85
	v_mul_f32_e32 v66, 0x3fb8aa3b, v66
	v_mul_f32_e32 v81, 0xbfb8aa3b, v81
	v_exp_f32_e32 v66, v66
	v_exp_f32_e32 v81, v81
	s_waitcnt lgkmcnt(0)
; __device__ __forceinline__ float softplusf_(float x) { return fmaxf(x, 0.f) + log1pf(__expf(-fabsf(x))); }
; #define LBAR0() do { asm volatile("s_waitcnt lgkmcnt(0)" ::: "memory"); __builtin_amdgcn_s_barrier(); asm volatile("" ::: "memory"); } while (0)
; __device__ __forceinline__ float fsig0(float x) { return __builtin_amdgcn_rcpf(1.0f + __expf(-x)); }
; template <int PASS> __device__ void lru_phase(const Params& p, unsigned char* smem) {
;     ...
;         {
;             const int ch = 16 * wave + (lane & 15), cgl = jb * 128 + ch;
;             const float ba_ = jb_fixed ? hb_a : p.in[6][cgl], bx_ = jb_fixed ? hb_x : p.in[8][cgl], sp = jb_fixed ? hsp : softplusf_(-p.in[9][cgl]);
; #pragma unroll
;             for (int m = 0; m < 4; ++m)
; #pragma unroll
;                 for (int r = 0; r < 4; ++r) { const int t = 16 * m + 4 * (lane >> 4) + r;
;                     const float rg = fsig0(accA[m][r] + ba_), ig = fsig0(accX[m][r] + bx_);
;                     const float la = -8.0f * rg * sp, a = __expf(la), u = __builtin_amdgcn_sqrtf(fmaxf(1.0f - a * a, 0.f)) * (ig * xcf[t * 132 + ch]);
;                     As[t * 132 + ch] = a; Us[t * 132 + ch] = u; }
;         }
;         LBAR0();
	v_mul_f32_e32 v84, v84, v86
	v_add_f32_e32 v76, v76, v101
	v_mul_f32_e32 v84, v85, v84
	v_mul_f32_e32 v76, 0xbfb8aa3b, v76
	v_exp_f32_e32 v76, v76
	ds_write_b32 v149, v84
	v_fma_f32 v80, -v66, v66, 1.0
	ds_write_b32 v141, v66 offset:50688
	v_add_f32_e32 v66, 1.0, v81
	v_rcp_f32_e32 v66, v66
	v_add_f32_e32 v76, 1.0, v76
	ds_read_b32 v84, v141 offset:16896
	v_rcp_f32_e32 v76, v76
	v_max_f32_e32 v80, 0, v80
	v_mul_f32_e32 v66, 0xc1000000, v66
	v_sqrt_f32_e32 v80, v80
	v_add_f32_e32 v77, v77, v101
	v_mul_f32_e32 v66, v66, v102
	v_add_f32_e32 v81, v82, v100
	v_mul_f32_e32 v77, 0xbfb8aa3b, v77
	v_mul_f32_e32 v66, 0x3fb8aa3b, v66
	v_mul_f32_e32 v81, 0xbfb8aa3b, v81
	v_exp_f32_e32 v77, v77
	v_exp_f32_e32 v66, v66
	v_exp_f32_e32 v81, v81
	s_waitcnt lgkmcnt(0)
	v_mul_f32_e32 v76, v76, v84
	v_mul_f32_e32 v76, v80, v76
	ds_write_b32 v150, v76
	v_add_f32_e32 v76, 1.0, v77
	v_fma_f32 v77, -v66, v66, 1.0
	ds_read_b32 v80, v141 offset:17424
	ds_write_b32 v141, v66 offset:51216
	v_add_f32_e32 v66, 1.0, v81
	v_rcp_f32_e32 v76, v76
	v_max_f32_e32 v77, 0, v77
	v_rcp_f32_e32 v66, v66
	v_sqrt_f32_e32 v77, v77
	s_waitcnt lgkmcnt(1)
	v_mul_f32_e32 v76, v76, v80
	v_add_f32_e32 v80, v83, v100
	v_mul_f32_e32 v66, 0xc1000000, v66
	v_mul_f32_e32 v76, v77, v76
	v_add_f32_e32 v77, v78, v101
	v_mul_f32_e32 v66, v66, v102
	v_mul_f32_e32 v77, 0xbfb8aa3b, v77
	v_mul_f32_e32 v66, 0x3fb8aa3b, v66
	v_mul_f32_e32 v80, 0xbfb8aa3b, v80
	v_exp_f32_e32 v77, v77
	v_exp_f32_e32 v66, v66
	v_exp_f32_e32 v80, v80
	ds_write_b32 v151, v76
	v_add_f32_e32 v76, 1.0, v77
	v_fma_f32 v77, -v66, v66, 1.0
	ds_read_b32 v78, v141 offset:17952
	ds_write_b32 v141, v66 offset:51744
	v_add_f32_e32 v66, 1.0, v80
	v_rcp_f32_e32 v76, v76
	v_max_f32_e32 v77, 0, v77
	v_rcp_f32_e32 v66, v66
	v_sqrt_f32_e32 v77, v77
	s_waitcnt lgkmcnt(1)
	v_mul_f32_e32 v76, v76, v78
	v_add_f32_e32 v72, v72, v100
	v_mul_f32_e32 v66, 0xc1000000, v66
	v_mul_f32_e32 v76, v77, v76
	v_add_f32_e32 v77, v79, v101
	v_mul_f32_e32 v66, v66, v102
	v_mul_f32_e32 v77, 0xbfb8aa3b, v77
	v_mul_f32_e32 v66, 0x3fb8aa3b, v66
	v_mul_f32_e32 v72, 0xbfb8aa3b, v72
	v_exp_f32_e32 v77, v77
	v_exp_f32_e32 v66, v66
	v_exp_f32_e32 v72, v72
	ds_write_b32 v152, v76
	v_add_f32_e32 v76, 1.0, v77
	v_fma_f32 v77, -v66, v66, 1.0
	ds_write_b32 v141, v66 offset:52272
	v_add_f32_e32 v66, 1.0, v72
	v_rcp_f32_e32 v66, v66
	ds_read_b32 v78, v141 offset:18480
	v_rcp_f32_e32 v76, v76
	v_max_f32_e32 v77, 0, v77
	v_mul_f32_e32 v66, 0xc1000000, v66
	v_mul_f32_e32 v66, v66, v102
	v_add_f32_e32 v73, v73, v100
	v_sqrt_f32_e32 v77, v77
	v_mul_f32_e32 v66, 0x3fb8aa3b, v66
	v_mul_f32_e32 v73, 0xbfb8aa3b, v73
	v_exp_f32_e32 v66, v66
	v_exp_f32_e32 v73, v73
	s_waitcnt lgkmcnt(0)
	v_mul_f32_e32 v76, v76, v78
	v_add_f32_e32 v68, v68, v101
	v_mul_f32_e32 v76, v77, v76
	v_mul_f32_e32 v68, 0xbfb8aa3b, v68
	v_exp_f32_e32 v68, v68
	ds_write_b32 v153, v76
	v_fma_f32 v72, -v66, v66, 1.0
	ds_write_b32 v141, v66 offset:59136
	v_add_f32_e32 v66, 1.0, v73
	v_rcp_f32_e32 v66, v66
	v_add_f32_e32 v68, 1.0, v68
	ds_read_b32 v76, v141 offset:25344
	v_rcp_f32_e32 v68, v68
	v_max_f32_e32 v72, 0, v72
	v_mul_f32_e32 v66, 0xc1000000, v66
	v_sqrt_f32_e32 v72, v72
	v_add_f32_e32 v69, v69, v101
	v_mul_f32_e32 v66, v66, v102
	v_add_f32_e32 v73, v74, v100
	v_mul_f32_e32 v69, 0xbfb8aa3b, v69
	v_mul_f32_e32 v66, 0x3fb8aa3b, v66
	v_mul_f32_e32 v73, 0xbfb8aa3b, v73
	v_exp_f32_e32 v69, v69
	v_exp_f32_e32 v66, v66
	v_exp_f32_e32 v73, v73
	s_waitcnt lgkmcnt(0)
	v_mul_f32_e32 v68, v68, v76
	v_mul_f32_e32 v68, v72, v68
	ds_write_b32 v154, v68
	v_add_f32_e32 v68, 1.0, v69
	v_fma_f32 v69, -v66, v66, 1.0
	ds_read_b32 v72, v141 offset:25872
	ds_write_b32 v141, v66 offset:59664
	v_add_f32_e32 v66, 1.0, v73
	v_rcp_f32_e32 v68, v68
	v_max_f32_e32 v69, 0, v69
	v_rcp_f32_e32 v66, v66
	v_sqrt_f32_e32 v69, v69
	s_waitcnt lgkmcnt(1)
	v_mul_f32_e32 v68, v68, v72
	v_add_f32_e32 v72, v75, v100
	v_mul_f32_e32 v66, 0xc1000000, v66
	v_mul_f32_e32 v68, v69, v68
	v_add_f32_e32 v69, v70, v101
	v_mul_f32_e32 v66, v66, v102
	v_mul_f32_e32 v69, 0xbfb8aa3b, v69
	v_mul_f32_e32 v66, 0x3fb8aa3b, v66
	v_mul_f32_e32 v72, 0xbfb8aa3b, v72
	v_exp_f32_e32 v69, v69
	v_exp_f32_e32 v66, v66
	v_exp_f32_e32 v72, v72
	ds_write_b32 v155, v68
	v_add_f32_e32 v68, 1.0, v69
	v_fma_f32 v69, -v66, v66, 1.0
	ds_read_b32 v70, v141 offset:26400
	ds_write_b32 v141, v66 offset:60192
	v_add_f32_e32 v66, 1.0, v72
	v_rcp_f32_e32 v68, v68
	v_max_f32_e32 v69, 0, v69
	v_rcp_f32_e32 v66, v66
	v_sqrt_f32_e32 v69, v69
	v_add_f32_e32 v92, v92, v101
	s_waitcnt lgkmcnt(1)
	v_mul_f32_e32 v68, v68, v70
	v_mul_f32_e32 v66, 0xc1000000, v66
	v_mul_f32_e32 v92, 0xbfb8aa3b, v92
	v_mul_f32_e32 v68, v69, v68
	v_add_f32_e32 v69, v71, v101
	v_mul_f32_e32 v66, v66, v102
	v_exp_f32_e32 v92, v92
	v_mul_f32_e32 v69, 0xbfb8aa3b, v69
	v_mul_f32_e32 v66, 0x3fb8aa3b, v66
	v_exp_f32_e32 v69, v69
	v_exp_f32_e32 v66, v66
	v_add_f32_e32 v92, 1.0, v92
	ds_write_b32 v156, v68
	v_rcp_f32_e32 v92, v92
	v_max_f32_e32 v97, 0, v97
	v_add_f32_e32 v68, 1.0, v69
	v_fma_f32 v69, -v66, v66, 1.0
	ds_read_b32 v70, v141 offset:26928
	v_sqrt_f32_e32 v97, v97
	v_rcp_f32_e32 v68, v68
	v_max_f32_e32 v69, 0, v69
	v_sqrt_f32_e32 v69, v69
	v_mul_f32_e32 v92, v92, v104
	v_mul_f32_e32 v71, v92, v97
	s_waitcnt lgkmcnt(0)
	v_mul_f32_e32 v68, v68, v70
	ds_write_b32 v142, v71
	v_mul_f32_e32 v68, v69, v68
	ds_write_b32 v141, v66 offset:60720
	ds_write_b32 v157, v68
	s_waitcnt lgkmcnt(0)
	s_barrier
; #define LBAR0() do { asm volatile("s_waitcnt lgkmcnt(0)" ::: "memory"); __builtin_amdgcn_s_barrier(); asm volatile("" ::: "memory"); } while (0)
; template <int PASS> __device__ void lru_phase(const Params& p, unsigned char* smem) {
;     ...
;         { float h = 0.f, A = 1.f;
; #pragma unroll
;           for (int tt = 0; tt < 16; ++tt) { const int t = q * 16 + tt; const float a = As[t * 132 + ch], u = Us[t * 132 + ch]; h = a * h + u; A *= a;
;               if (PASS == 2) { Us[t * 132 + ch] = h; As[t * 132 + ch] = A; } }
;           qA[q * 128 + ch] = A; qH[q * 128 + ch] = h; }
;         LBAR0();
;         if (PASS == 1) {
;             if (q == 0) { float h = 0.f, A = 1.f;
; #pragma unroll
;                 for (int qq = 0; qq < 4; ++qq) { h = qA[qq * 128 + ch] * h + qH[qq * 128 + ch]; A *= qA[qq * 128 + ch]; }
;                 LA[(size_t)(b * 64 + c) * 2048 + cgl] = A; LH[(size_t)(b * 64 + c) * 2048 + cgl] = h; }
;         } else {
;             float carry = LC[(size_t)(b * 64 + c) * 2048 + cgl];
;             for (int qq = 0; qq < q; ++qq) carry = qA[qq * 128 + ch] * carry + qH[qq * 128 + ch];
	ds_read_b32 v66, v158 offset:33792
	ds_read_b32 v68, v1
	s_lshl_b32 s4, s25, 6
	s_or_b32 s4, s4, s24
	s_ashr_i32 s5, s4, 31
	s_lshl_b64 s[4:5], s[4:5], 13
	s_waitcnt lgkmcnt(0)
	v_fmac_f32_e32 v68, 0, v66
	ds_write_b32 v1, v68
	ds_read_b32 v69, v160 offset:33792
	ds_read_b32 v70, v161
	s_add_u32 s4, s26, s4
	s_addc_u32 s5, s27, s5
	s_waitcnt lgkmcnt(1)
	v_mul_f32_e32 v66, v66, v69
	s_waitcnt lgkmcnt(0)
	v_fmac_f32_e32 v70, v68, v69
	ds_write_b32 v161, v70
	ds_write_b32 v160, v66 offset:33792
	ds_read_b32 v68, v163 offset:33792
	ds_read_b32 v69, v164
	s_waitcnt lgkmcnt(1)
	v_mul_f32_e32 v66, v66, v68
	s_waitcnt lgkmcnt(0)
	v_fmac_f32_e32 v69, v70, v68
	ds_write_b32 v164, v69
	ds_write_b32 v163, v66 offset:33792
	ds_read_b32 v68, v166 offset:33792
	ds_read_b32 v70, v167
	s_waitcnt lgkmcnt(1)
	v_mul_f32_e32 v66, v66, v68
	s_waitcnt lgkmcnt(0)
	v_fmac_f32_e32 v70, v69, v68
	ds_write_b32 v167, v70
	ds_write_b32 v166, v66 offset:33792
	ds_read_b32 v68, v169 offset:33792
	ds_read_b32 v69, v170
	s_waitcnt lgkmcnt(1)
	v_mul_f32_e32 v66, v66, v68
	s_waitcnt lgkmcnt(0)
	v_fmac_f32_e32 v69, v70, v68
	ds_write_b32 v170, v69
	ds_write_b32 v169, v66 offset:33792
	ds_read_b32 v68, v172 offset:33792
	ds_read_b32 v70, v173
	s_waitcnt lgkmcnt(1)
	v_mul_f32_e32 v66, v66, v68
	s_waitcnt lgkmcnt(0)
	v_fmac_f32_e32 v70, v69, v68
	ds_write_b32 v173, v70
	ds_write_b32 v172, v66 offset:33792
	ds_read_b32 v68, v175 offset:33792
	ds_read_b32 v69, v176
	s_waitcnt lgkmcnt(1)
	v_mul_f32_e32 v66, v66, v68
	s_waitcnt lgkmcnt(0)
	v_fmac_f32_e32 v69, v70, v68
	ds_write_b32 v176, v69
	ds_write_b32 v175, v66 offset:33792
	ds_read_b32 v68, v178 offset:33792
	ds_read_b32 v70, v179
	s_waitcnt lgkmcnt(1)
	v_mul_f32_e32 v66, v66, v68
	s_waitcnt lgkmcnt(0)
	v_fmac_f32_e32 v70, v69, v68
	ds_write_b32 v179, v70
	ds_write_b32 v178, v66 offset:33792
	ds_read_b32 v68, v181 offset:33792
	ds_read_b32 v69, v182
	s_waitcnt lgkmcnt(1)
	v_mul_f32_e32 v66, v66, v68
	s_waitcnt lgkmcnt(0)
	v_fmac_f32_e32 v69, v70, v68
	ds_write_b32 v182, v69
	ds_write_b32 v181, v66 offset:33792
	ds_read_b32 v68, v184 offset:33792
	ds_read_b32 v70, v185
	s_waitcnt lgkmcnt(1)
	v_mul_f32_e32 v66, v66, v68
	s_waitcnt lgkmcnt(0)
	v_fmac_f32_e32 v70, v69, v68
	ds_write_b32 v185, v70
	ds_write_b32 v184, v66 offset:33792
	ds_read_b32 v68, v187 offset:33792
	ds_read_b32 v69, v188
	s_waitcnt lgkmcnt(1)
	v_mul_f32_e32 v66, v66, v68
	s_waitcnt lgkmcnt(0)
	v_fmac_f32_e32 v69, v70, v68
	ds_write_b32 v188, v69
	ds_write_b32 v187, v66 offset:33792
	ds_read_b32 v68, v190 offset:33792
	ds_read_b32 v70, v191
	s_waitcnt lgkmcnt(1)
	v_mul_f32_e32 v66, v66, v68
	s_waitcnt lgkmcnt(0)
	v_fmac_f32_e32 v70, v69, v68
	ds_write_b32 v191, v70
	ds_write_b32 v190, v66 offset:33792
	ds_read_b32 v68, v193 offset:33792
	ds_read_b32 v69, v194
	s_waitcnt lgkmcnt(1)
	v_mul_f32_e32 v66, v66, v68
	s_waitcnt lgkmcnt(0)
	v_fmac_f32_e32 v69, v70, v68
	ds_write_b32 v194, v69
	ds_write_b32 v193, v66 offset:33792
	ds_read_b32 v68, v196 offset:33792
	ds_read_b32 v70, v197
	s_waitcnt lgkmcnt(1)
	v_mul_f32_e32 v66, v66, v68
	s_waitcnt lgkmcnt(0)
	v_fmac_f32_e32 v70, v69, v68
	ds_write_b32 v197, v70
	ds_write_b32 v196, v66 offset:33792
	ds_read_b32 v68, v199 offset:33792
	ds_read_b32 v69, v200
	s_waitcnt lgkmcnt(1)
	v_mul_f32_e32 v66, v66, v68
	s_waitcnt lgkmcnt(0)
	v_fmac_f32_e32 v69, v70, v68
	ds_write_b32 v200, v69
	ds_write_b32 v199, v66 offset:33792
	ds_read_b32 v68, v202 offset:33792
	ds_read_b32 v70, v203
	s_waitcnt lgkmcnt(0)
	v_fmac_f32_e32 v70, v69, v68
	v_mul_f32_e32 v68, v66, v68
	ds_write_b32 v203, v70
	ds_write_b32 v202, v68 offset:33792
	v_or_b32_e32 v66, s39, v132
	ds_write_b32 v139, v68
	ds_write_b32 v140, v70
	s_waitcnt lgkmcnt(0)
	s_barrier
	v_lshlrev_b32_e32 v68, 2, v66
	v_bfe_u32 v85, v0, 6, 3
	s_sub_i32 s40, s37, s62
	s_bfe_u32 s41, s40, 0x60004
	s_lshr_b32 s42, s40, 10
	s_and_b32 s43, s40, 15
	v_readfirstlane_b32 s47, v85
	s_lshl_b32 s44, s42, 6
	s_or_b32 s44, s44, s41
	s_cmp_lt_u32 s47, 2
	s_cbranch_scc0 LRUX_join
	s_add_u32 s48, s64, 0x1f100000
	s_addc_u32 s49, s65, 0
	s_add_u32 s52, s64, 0x1f500000
	s_addc_u32 s53, s65, 0
	v_add_u32_e32 v71, 0xfffff800, v205
	ds_read_b32 v72, v71
	ds_read_b32 v73, v71 offset:512
	ds_read_b32 v74, v71 offset:1024
	ds_read_b32 v75, v71 offset:1536
	ds_read_b32 v76, v71 offset:2048
	ds_read_b32 v77, v71 offset:2560
	ds_read_b32 v78, v71 offset:3072
	ds_read_b32 v79, v71 offset:3584
	s_lshl_b32 s45, s44, 14
	v_lshl_add_u32 v82, v66, 3, s45
	s_and_b32 s46, s47, 1
	s_lshl_b32 s54, s43, 3
	s_lshl_b32 s46, s46, 2
	s_add_i32 s54, s54, s46
	s_waitcnt lgkmcnt(0)
	v_fma_f32 v81, v73, v76, v77
	v_mul_f32_e32 v80, v72, v73
	v_fma_f32 v81, v74, v81, v78
	v_mul_f32_e32 v80, v80, v74
	v_fma_f32 v81, v75, v81, v79
	v_mul_f32_e32 v80, v80, v75
	global_store_dwordx2 v82, v[80:81], s[48:49] sc0 sc1
	s_lshl_b32 s46, s44, 7
	s_add_i32 s46, s46, s54
	v_mov_b32_e32 v83, 1
	v_mov_b32_e32 v84, s46
	s_waitcnt vmcnt(0)
	global_store_dword v84, v83, s[52:53] sc0 sc1
	s_cmp_lt_u32 s41, 16
	s_cbranch_scc0 LRUX_keepP
	v_mov_b32_e32 v252, 0

; template <int PASS> __device__ void lru_phase(const Params& p, unsigned char* smem) {
;     ...
;             if (q == 0) { float h = 0.f, A = 1.f;
; #pragma unroll
;                 for (int qq = 0; qq < 4; ++qq) { h = qA[qq * 128 + ch] * h + qH[qq * 128 + ch]; A *= qA[qq * 128 + ch]; }
;                 LA[(size_t)(b * 64 + c) * 2048 + cgl] = A; LH[(size_t)(b * 64 + c) * 2048 + cgl] = h; }
;         } else {
;             float carry = LC[(size_t)(b * 64 + c) * 2048 + cgl];
;             for (int qq = 0; qq < q; ++qq) carry = qA[qq * 128 + ch] * carry + qH[qq * 128 + ch];
LRUX_polled:
	s_cmp_lt_u32 s41, 1
	s_cselect_b32 s58, 0, 0x4000
	v_subrev_u32_e32 v87, s58, v82
	global_load_dwordx2 v[98:99], v87, s[48:49] sc0 sc1
	s_cmp_lt_u32 s41, 2
	s_cselect_b32 s58, 0, 0x8000
	v_subrev_u32_e32 v87, s58, v82
	global_load_dwordx2 v[100:101], v87, s[48:49] sc0 sc1
	s_cmp_lt_u32 s41, 3
	s_cselect_b32 s58, 0, 0xc000
	v_subrev_u32_e32 v87, s58, v82
	global_load_dwordx2 v[102:103], v87, s[48:49] sc0 sc1
	s_cmp_lt_u32 s41, 4
	s_cselect_b32 s58, 0, 0x10000
	v_subrev_u32_e32 v87, s58, v82
	global_load_dwordx2 v[104:105], v87, s[48:49] sc0 sc1
	s_cmp_lt_u32 s41, 5
	s_cselect_b32 s58, 0, 0x14000
	v_subrev_u32_e32 v87, s58, v82
	global_load_dwordx2 v[106:107], v87, s[48:49] sc0 sc1
	s_cmp_lt_u32 s41, 6
	s_cselect_b32 s58, 0, 0x18000
	v_subrev_u32_e32 v87, s58, v82
	global_load_dwordx2 v[108:109], v87, s[48:49] sc0 sc1
	s_cmp_lt_u32 s41, 7
	s_cselect_b32 s58, 0, 0x1c000
	v_subrev_u32_e32 v87, s58, v82
	global_load_dwordx2 v[110:111], v87, s[48:49] sc0 sc1
	s_cmp_lt_u32 s41, 8
	s_cselect_b32 s58, 0, 0x20000
	v_subrev_u32_e32 v87, s58, v82
	global_load_dwordx2 v[112:113], v87, s[48:49] sc0 sc1
	s_cmp_lt_u32 s41, 9
	s_cselect_b32 s58, 0, 0x24000
	v_subrev_u32_e32 v87, s58, v82
	global_load_dwordx2 v[114:115], v87, s[48:49] sc0 sc1
	s_cmp_lt_u32 s41, 10
	s_cselect_b32 s58, 0, 0x28000
	v_subrev_u32_e32 v87, s58, v82
	global_load_dwordx2 v[116:117], v87, s[48:49] sc0 sc1
	s_cmp_lt_u32 s41, 11
	s_cselect_b32 s58, 0, 0x2c000
	v_subrev_u32_e32 v87, s58, v82
	global_load_dwordx2 v[118:119], v87, s[48:49] sc0 sc1
	s_cmp_lt_u32 s41, 12
	s_cselect_b32 s58, 0, 0x30000
	v_subrev_u32_e32 v87, s58, v82
	global_load_dwordx2 v[120:121], v87, s[48:49] sc0 sc1
	s_cmp_lt_u32 s41, 13
	s_cselect_b32 s58, 0, 0x34000
	v_subrev_u32_e32 v87, s58, v82
	global_load_dwordx2 v[122:123], v87, s[48:49] sc0 sc1
	s_cmp_lt_u32 s41, 14
	s_cselect_b32 s58, 0, 0x38000
	v_subrev_u32_e32 v87, s58, v82
	global_load_dwordx2 v[228:229], v87, s[48:49] sc0 sc1
	s_cmp_lt_u32 s41, 15
	s_cselect_b32 s58, 0, 0x3c000
	v_subrev_u32_e32 v87, s58, v82
	global_load_dwordx2 v[230:231], v87, s[48:49] sc0 sc1
	s_waitcnt vmcnt(0)
	v_mov_b32_e32 v70, v252
	s_cmp_lt_u32 s41, 15
	s_cbranch_scc1 LRUX_sk15
	v_fma_f32 v70, v230, v70, v231
LRUX_sk15:
	s_cmp_lt_u32 s41, 14
	s_cbranch_scc1 LRUX_sk14
	v_fma_f32 v70, v228, v70, v229
LRUX_sk14:
	s_cmp_lt_u32 s41, 13
	s_cbranch_scc1 LRUX_sk13
	v_fma_f32 v70, v122, v70, v123
LRUX_sk13:
	s_cmp_lt_u32 s41, 12
	s_cbranch_scc1 LRUX_sk12
	v_fma_f32 v70, v120, v70, v121
LRUX_sk12:
	s_cmp_lt_u32 s41, 11
	s_cbranch_scc1 LRUX_sk11
	v_fma_f32 v70, v118, v70, v119
LRUX_sk11:
	s_cmp_lt_u32 s41, 10
	s_cbranch_scc1 LRUX_sk10
	v_fma_f32 v70, v116, v70, v117
LRUX_sk10:
	s_cmp_lt_u32 s41, 9
	s_cbranch_scc1 LRUX_sk9
	v_fma_f32 v70, v114, v70, v115
LRUX_sk9:
	s_cmp_lt_u32 s41, 8
	s_cbranch_scc1 LRUX_sk8
	v_fma_f32 v70, v112, v70, v113
LRUX_sk8:
	s_cmp_lt_u32 s41, 7
	s_cbranch_scc1 LRUX_sk7
	v_fma_f32 v70, v110, v70, v111
LRUX_sk7:
	s_cmp_lt_u32 s41, 6
	s_cbranch_scc1 LRUX_sk6
	v_fma_f32 v70, v108, v70, v109
LRUX_sk6:
	s_cmp_lt_u32 s41, 5
	s_cbranch_scc1 LRUX_sk5
	v_fma_f32 v70, v106, v70, v107
LRUX_sk5:
	s_cmp_lt_u32 s41, 4
	s_cbranch_scc1 LRUX_sk4
	v_fma_f32 v70, v104, v70, v105
LRUX_sk4:
	s_cmp_lt_u32 s41, 3
	s_cbranch_scc1 LRUX_sk3
	v_fma_f32 v70, v102, v70, v103
LRUX_sk3:
	s_cmp_lt_u32 s41, 2
	s_cbranch_scc1 LRUX_sk2
	v_fma_f32 v70, v100, v70, v101
LRUX_sk2:
	s_cmp_lt_u32 s41, 1
	s_cbranch_scc1 LRUX_sk1
	v_fma_f32 v70, v98, v70, v99
LRUX_sk1:
	v_fma_f32 v252, v80, v70, v81
	ds_write_b32 v205, v70 offset:6144
LRUX_join:
	s_waitcnt lgkmcnt(0)
	s_barrier
	ds_read_b32 v70, v205 offset:6144
	s_waitcnt lgkmcnt(0)
	s_and_saveexec_b64 s[4:5], s[2:3]
	s_cbranch_execz .LBB0_541
	s_mov_b64 s[24:25], 0
	v_mov_b32_e32 v68, v205
	v_mov_b32_e32 v69, v137
